# weight conversion spread over idle workgroups: one shared routine at the phase-loop head converts layer-1 qkv/v/out in phase 6, w13 in phase 8, w2 in phase 11 (workgroups 128..255) and layer-0 w2 in p
# speedup vs baseline: 1.0103x; 1.0039x over previous
.LBB0_22:
	s_load_dword vcc_lo, s[100:101], 0xc0
	s_waitcnt lgkmcnt(0)
	s_cmp_eq_u32 vcc_lo, 0x100
	s_cbranch_scc0 .Lwt1_skip
	s_cmp_eq_u32 s66, 6
	s_cbranch_scc0 .Lwt1_n0
	s_cmp_ge_u32 s99, 128
	s_cbranch_scc0 .Lwt1_skip
	s_mov_b32 vcc_lo, 0x0
	s_mov_b32 vcc_hi, 0x280
	s_mov_b32 s98, 0x800080
	s_branch .Lwt1_go
.Lwt1_n0:
	s_cmp_eq_u32 s66, 8
	s_cbranch_scc0 .Lwt1_n1
	s_cmp_ge_u32 s99, 128
	s_cbranch_scc0 .Lwt1_skip
	s_mov_b32 vcc_lo, 0x280
	s_mov_b32 vcc_hi, 0x800
	s_mov_b32 s98, 0x800080
	s_branch .Lwt1_go
.Lwt1_n1:
	s_cmp_eq_u32 s66, 11
	s_cbranch_scc0 .Lwt1_n2
	s_cmp_ge_u32 s99, 128
	s_cbranch_scc0 .Lwt1_skip
	s_mov_b32 vcc_lo, 0x800
	s_mov_b32 vcc_hi, 0xac0
	s_mov_b32 s98, 0x800080
	s_branch .Lwt1_go
.Lwt1_n2:
	s_cmp_eq_u32 s66, 1
	s_cbranch_scc0 .Lwt1_n3
	s_cmp_ge_u32 s99, 192
	s_cbranch_scc0 .Lwt1_skip
	s_mov_b32 vcc_lo, 0xac0
	s_mov_b32 vcc_hi, 0xd80
	s_mov_b32 s98, 0xc00040
	s_branch .Lwt1_go

.Lwt1_go:
	s_mov_b64 exec, -1
	v_writelane_b32 v59, s16, 0
	v_writelane_b32 v59, s17, 1
	v_writelane_b32 v59, s18, 2
	v_writelane_b32 v59, s19, 3
	v_writelane_b32 v59, s20, 4
	v_writelane_b32 v59, s21, 5
	v_writelane_b32 v59, s22, 6
	v_writelane_b32 v59, s23, 7
	v_writelane_b32 v59, s24, 8
	v_writelane_b32 v59, s25, 9
	v_writelane_b32 v59, s26, 10
	v_writelane_b32 v59, s27, 11
	v_writelane_b32 v59, s28, 12
	v_writelane_b32 v59, s29, 13
	v_writelane_b32 v59, s30, 14
	v_writelane_b32 v59, s31, 15
	v_writelane_b32 v59, s32, 16
	v_writelane_b32 v59, s33, 17
	v_writelane_b32 v59, s34, 18
	v_writelane_b32 v59, s35, 19
	v_writelane_b32 v59, s36, 20
	v_writelane_b32 v59, s37, 21
	v_writelane_b32 v59, s38, 22
	v_writelane_b32 v59, s39, 23
	v_writelane_b32 v59, s40, 24
	v_writelane_b32 v59, s41, 25
	v_writelane_b32 v59, s42, 26
	v_writelane_b32 v59, s43, 27
	v_writelane_b32 v59, s44, 28
	v_writelane_b32 v59, s45, 29
	v_writelane_b32 v59, s46, 30
	v_writelane_b32 v59, s47, 31
	v_writelane_b32 v59, s48, 32
	v_writelane_b32 v59, s49, 33
	v_writelane_b32 v59, s50, 34
	v_writelane_b32 v59, s51, 35
	v_writelane_b32 v59, s52, 36
	v_writelane_b32 v59, s53, 37
	v_writelane_b32 v59, s54, 38
	v_writelane_b32 v59, s55, 39
	s_memrealtime s[40:41]
	s_waitcnt lgkmcnt(0)
	s_add_u32 s42, s40, 1000
.Lwt1_spin:
	s_sleep 4
	s_memrealtime s[40:41]
	s_waitcnt lgkmcnt(0)
	s_sub_u32 s43, s40, s42
	s_cmp_lt_i32 s43, 0
	s_cbranch_scc1 .Lwt1_spin
	v_lshrrev_b32_e32 v60, 6, v225
	v_and_b32_e32 v61, 63, v225
	v_and_b32_e32 v62, 32, v225
	s_load_dwordx2 s[44:45], s[100:101], 0xb0
	v_readfirstlane_b32 s16, v60
	v_add_u32_e32 v62, v62, v61
	v_lshlrev_b32_e32 v60, 2, v61
	s_waitcnt lgkmcnt(0)
	s_mov_b32 s52, vcc_lo
	s_mov_b32 s53, vcc_hi
	s_lshr_b32 s54, s98, 16
	s_and_b32 s17, s98, 0xffff
	s_lshl_b32 s17, s17, 3
	s_sub_u32 s18, s99, s54
	s_lshl_b32 s18, s18, 3
	s_add_u32 s18, s18, s52
	s_add_u32 s16, s16, s18
.Lwt1_loop:
	s_cmp_ge_u32 s16, s53
	s_cbranch_scc1 .Lwt1_done
	s_cmp_lt_u32 s16, 0x140
	s_cbranch_scc1 .Lwt1_d0
	s_cmp_lt_u32 s16, 0x180
	s_cbranch_scc1 .Lwt1_d1
	s_cmp_lt_u32 s16, 0x280
	s_cbranch_scc1 .Lwt1_d2
	s_cmp_lt_u32 s16, 0x800
	s_cbranch_scc1 .Lwt1_d3
	s_cmp_lt_u32 s16, 0xac0
	s_cbranch_scc1 .Lwt1_d4
	s_branch .Lwt1_d5

.Lwt1_d5:
	s_sub_u32 s19, s16, 0xac0
	s_mov_b32 s46, 0xa0
	s_mov_b32 s47, 0x0
	s_mov_b32 s48, 0x0
	s_mov_b32 s49, 0x0
	s_mov_b32 s50, 0x1780000
	s_mov_b32 s51, 0
	s_mov_b32 s26, 0x1000
	s_mov_b32 s39, 0x40000
	s_mov_b32 s27, 0x1600
	s_mov_b32 s28, 0x10
	s_mov_b32 s29, 0x10000000
	s_mov_b32 s30, 0
	s_mov_b32 s31, 0x0
	s_branch .Lwt1_common

.Lwt0_loop:
	s_cmp_ge_u32 s16, 0xbc0
	s_cbranch_scc1 .Lwt0_done
	s_cmp_lt_u32 s16, 0x440
	s_cbranch_scc1 .Lwt0_d0
	s_cmp_lt_u32 s16, 0x4c0
	s_cbranch_scc1 .Lwt0_d1
	s_cmp_lt_u32 s16, 0x640
	s_cbranch_scc1 .Lwt0_d2
	s_branch .Lwt0_d3

.Lwt0_d3:
	s_sub_u32 s19, s16, 0x640
	s_mov_b32 s46, 0x98
	s_mov_b32 s47, 0x0
	s_mov_b32 s48, 0x90
	s_mov_b32 s49, 0x0
	s_mov_b32 s50, 0xc80000
	s_mov_b32 s51, 1
	s_mov_b32 s26, 0x5800
	s_mov_b32 s39, 0x160000
	s_mov_b32 s27, 0x800
	s_mov_b32 s28, 0x58
	s_mov_b32 s29, 0x2e8ba2f
	s_mov_b32 s30, 1
	s_mov_b32 s31, 0x0
	s_branch .Lwt0_common
.Lwt0_common:
	s_load_dwordx2 s[20:21], s[100:101], s46
	s_cmp_lg_u32 s51, 0
	s_cbranch_scc0 .Lwt0_nog0
	s_load_dwordx2 s[22:23], s[100:101], s48
